# grid sync A->B in layer 1 now uses the flat-counter barrier (layer 0 keeps the cooperative-groups one); bias1 restructure kept
# speedup vs baseline: 1.0317x; 1.0077x over previous
; __global__ void __launch_bounds__(512, 2) hybrid_fwd(Params P) {
;     ...
;         grid.sync();
.LBB0_413:
	s_or_b64 exec, exec, s[4:5]
	s_waitcnt vmcnt(0) lgkmcnt(0)
	s_barrier
	s_mov_b64 s[4:5], exec
	v_readlane_b32 s6, v255, 5
	v_readlane_b32 s7, v255, 6
	s_and_b64 s[6:7], s[4:5], s[6:7]
	s_xor_b64 s[4:5], s[6:7], s[4:5]
	s_mov_b64 exec, s[6:7]
	s_cbranch_execz .LBB0_423
	v_readlane_b32 s8, v255, 17
	s_cmp_eq_u32 s8, 0
	s_cbranch_scc1 .Lgb_cg_0
	buffer_wbl2 sc1
	s_waitcnt vmcnt(0)
	v_readlane_b32 s8, v255, 17
	v_mov_b32_e32 v1, 0
	v_mov_b32_e32 v0, 1
	s_lshl_b32 s8, s8, 5
	s_add_u32 s6, s58, s8
	s_addc_u32 s7, s59, 0
	s_mov_b32 s10, 0
	global_atomic_add v1, v0, s[6:7] offset:64
.Lgb_poll_0:
	global_load_dword v2, v1, s[6:7] offset:64 sc1
	s_waitcnt vmcnt(0)
	v_readfirstlane_b32 s8, v2
	s_cmp_ge_u32 s8, s69
	s_cbranch_scc1 .Lgb_done_0
	s_add_u32 s10, s10, 1
	s_cmp_gt_u32 s10, 0x40000
	s_cbranch_scc1 .Lgb_done_0
	s_sleep 1
	s_branch .Lgb_poll_0
.Lgb_done_0:
	buffer_inv sc1
	s_waitcnt vmcnt(0)
	s_branch .LBB0_423
